# attention main loops: drop no-op lgkmcnt waits, add-0, m0 save/restore, canonicalizing v_max
# speedup vs baseline: 1.0033x; 1.0024x over previous
.LBB0_644:
	v_add_u32_e32 v181, s44, v203
	ds_read_b64_tr_b16 v[176:177], v181 offset:24576
	ds_read_b64_tr_b16 v[178:179], v181 offset:25088
	v_mfma_f32_32x32x16_bf16 v[96:111], v[172:175], v[140:143], v[32:47]
	v_add_f32_e32 v80, v64, v65
	v_add_f32_e32 v80, v66, v80
	v_add_f32_e32 v80, v67, v80
	v_add_f32_e32 v80, v68, v80
	v_add_f32_e32 v80, v69, v80
	v_cvt_pk_bf16_f32 v136, v64, v65
	v_cvt_pk_bf16_f32 v137, v66, v67
	ds_read_b64_tr_b16 v[172:173], v181 offset:28672
	ds_read_b64_tr_b16 v[174:175], v181 offset:29184
	v_add_f32_e32 v64, v70, v80
	v_mfma_f32_32x32x16_bf16 v[80:95], v[168:171], v[140:143], v[32:47]
	v_add_f32_e32 v64, v71, v64
	v_add_f32_e32 v64, v72, v64
	v_add_f32_e32 v116, v73, v64
	v_cvt_pk_bf16_f32 v138, v68, v69
	v_cvt_pk_bf16_f32 v139, v70, v71
	ds_read_b64_tr_b16 v[64:65], v181 offset:25600
	ds_read_b64_tr_b16 v[66:67], v181 offset:26112
	v_mfma_f32_32x32x16_bf16 v[96:111], v[164:167], v[132:135], v[96:111]
	v_add_f32_e32 v68, v74, v116
	v_add_f32_e32 v68, v75, v68
	v_add_f32_e32 v68, v76, v68
	v_add_f32_e32 v116, v77, v68
	v_cvt_pk_bf16_f32 v128, v72, v73
	v_cvt_pk_bf16_f32 v129, v74, v75
	ds_read_b64_tr_b16 v[68:69], v181 offset:29696
	ds_read_b64_tr_b16 v[70:71], v181 offset:30208
	v_mfma_f32_32x32x16_bf16 v[80:95], v[160:163], v[132:135], v[80:95]
	v_add_f32_e32 v72, v78, v116
	v_add_f32_e32 v72, v79, v72
	v_add_f32_e32 v72, v48, v72
	v_add_f32_e32 v116, v49, v72
	v_cvt_pk_bf16_f32 v130, v76, v77
	v_cvt_pk_bf16_f32 v131, v78, v79
	ds_read_b64_tr_b16 v[72:73], v181 offset:26624
	ds_read_b64_tr_b16 v[74:75], v181 offset:27136
	v_mfma_f32_32x32x16_bf16 v[96:111], v[156:159], v[120:123], v[96:111]
	v_add_f32_e32 v76, v50, v116
	v_add_f32_e32 v76, v51, v76
	v_add_f32_e32 v76, v52, v76
	v_add_f32_e32 v76, v53, v76
	v_cvt_pk_bf16_f32 v124, v48, v49
	v_cvt_pk_bf16_f32 v125, v50, v51
	ds_read_b64_tr_b16 v[48:49], v181 offset:30720
	ds_read_b64_tr_b16 v[50:51], v181 offset:31232
	v_mfma_f32_32x32x16_bf16 v[80:95], v[152:155], v[120:123], v[80:95]
	v_add_f32_e32 v76, v54, v76
	v_add_f32_e32 v76, v55, v76
	v_add_f32_e32 v76, v56, v76
	v_add_f32_e32 v76, v57, v76
	v_cvt_pk_bf16_f32 v126, v52, v53
	v_cvt_pk_bf16_f32 v127, v54, v55
	ds_read_b64_tr_b16 v[52:53], v181 offset:27648
	ds_read_b64_tr_b16 v[54:55], v181 offset:28160
	v_mfma_f32_32x32x16_bf16 v[96:111], v[148:151], v[112:115], v[96:111]
	v_add_f32_e32 v76, v58, v76
	v_add_f32_e32 v76, v59, v76
	v_add_f32_e32 v76, v60, v76
	v_add_f32_e32 v76, v61, v76
	v_cvt_pk_bf16_f32 v116, v56, v57
	v_cvt_pk_bf16_f32 v117, v58, v59
	ds_read_b64_tr_b16 v[56:57], v181 offset:31744
	ds_read_b64_tr_b16 v[58:59], v181 offset:32256
	v_mfma_f32_32x32x16_bf16 v[80:95], v[144:147], v[112:115], v[80:95]
	v_add_f32_e32 v76, v62, v76
	v_add_f32_e32 v76, v63, v76
	v_cvt_pk_bf16_f32 v118, v60, v61
	v_cvt_pk_bf16_f32 v119, v62, v63
	v_lshl_add_u64 v[186:187], v[184:185], 0, s[42:43]
	v_lshl_add_u64 v[60:61], v[186:187], 0, s[76:77]
	s_add_i32 s44, s70, s35
	s_mov_b32 m0, s44
	s_nop 0
	global_load_lds_dwordx4 v[60:61], off
	v_lshl_add_u64 v[188:189], v[182:183], 0, s[42:43]
	s_mov_b64 s[44:45], 0x15204000
	v_lshl_add_u64 v[60:61], v[188:189], 0, s[44:45]
	s_add_i32 s44, s68, s49
	s_mov_b32 m0, s44
	s_nop 0
	global_load_lds_dwordx4 v[60:61], off
	v_max_f32_e32 v60, v96, v97
	v_max3_f32 v61, v98, v99, v81
	v_max3_f32 v60, v60, v80, v82
	v_max3_f32 v60, v60, v83, v100
	v_max3_f32 v61, v61, v102, v103
	v_max3_f32 v60, v60, v101, v84
	v_max3_f32 v61, v61, v86, v87
	v_max3_f32 v60, v60, v85, v104
	v_max3_f32 v61, v61, v106, v107
	v_max3_f32 v60, v60, v105, v88
	v_max3_f32 v61, v61, v90, v91
	v_max3_f32 v60, v60, v89, v108
	v_max3_f32 v61, v61, v110, v111
	v_max3_f32 v60, v60, v109, v92
	v_max3_f32 v61, v61, v94, v95
	v_max3_f32 v60, v60, v93, v61
	v_mov_b32_e32 v61, v60
	s_nop 1
	v_permlane32_swap_b32_e32 v60, v61
	v_max_f32_e32 v60, v60, v61
	v_cmp_lt_f32_e32 vcc, s29, v60
	s_cmp_lg_u64 vcc, 0
	v_add_f32_e32 v191, v192, v76
	s_cselect_b64 s[44:45], -1, 0
	s_cbranch_vccnz .LBB0_652

.LBB0_647:
	s_add_i32 s44, s68, 0x2000
	s_cmpk_lg_i32 s68, 0x4000
	s_cselect_b32 s60, s44, 0
	v_add_u32_e32 v192, s70, v203
	ds_read_b64_tr_b16 v[148:149], v192 offset:24576
	ds_read_b64_tr_b16 v[150:151], v192 offset:25088
	v_mfma_f32_32x32x16_bf16 v[64:79], v[60:63], v[140:143], v[32:47]
	v_add_f32_e32 v48, v96, v97
	v_add_f32_e32 v48, v98, v48
	v_add_f32_e32 v48, v99, v48
	v_add_f32_e32 v48, v100, v48
	v_add_f32_e32 v48, v101, v48
	v_cvt_pk_bf16_f32 v136, v96, v97
	v_cvt_pk_bf16_f32 v137, v98, v99
	ds_read_b64_tr_b16 v[144:145], v192 offset:28672
	ds_read_b64_tr_b16 v[146:147], v192 offset:29184
	v_add_f32_e32 v48, v102, v48
	v_add_f32_e32 v48, v103, v48
	v_add_f32_e32 v48, v104, v48
	v_add_f32_e32 v116, v105, v48
	v_mfma_f32_32x32x16_bf16 v[48:63], v[172:175], v[140:143], v[32:47]
	v_cvt_pk_bf16_f32 v138, v100, v101
	v_cvt_pk_bf16_f32 v139, v102, v103
	ds_read_b64_tr_b16 v[96:97], v192 offset:25600
	ds_read_b64_tr_b16 v[98:99], v192 offset:26112
	v_mfma_f32_32x32x16_bf16 v[64:79], v[176:179], v[132:135], v[64:79]
	v_add_f32_e32 v100, v106, v116
	v_add_f32_e32 v100, v107, v100
	v_add_f32_e32 v100, v108, v100
	v_add_f32_e32 v116, v109, v100
	v_cvt_pk_bf16_f32 v128, v104, v105
	v_cvt_pk_bf16_f32 v129, v106, v107
	ds_read_b64_tr_b16 v[100:101], v192 offset:29696
	ds_read_b64_tr_b16 v[102:103], v192 offset:30208
	v_mfma_f32_32x32x16_bf16 v[48:63], v[168:171], v[132:135], v[48:63]
	v_add_f32_e32 v104, v110, v116
	v_add_f32_e32 v104, v111, v104
	v_add_f32_e32 v104, v80, v104
	v_add_f32_e32 v116, v81, v104
	v_cvt_pk_bf16_f32 v130, v108, v109
	v_cvt_pk_bf16_f32 v131, v110, v111
	ds_read_b64_tr_b16 v[104:105], v192 offset:26624
	ds_read_b64_tr_b16 v[106:107], v192 offset:27136
	v_mfma_f32_32x32x16_bf16 v[64:79], v[164:167], v[120:123], v[64:79]
	v_add_f32_e32 v108, v82, v116
	v_add_f32_e32 v108, v83, v108
	v_add_f32_e32 v108, v84, v108
	v_add_f32_e32 v108, v85, v108
	v_cvt_pk_bf16_f32 v124, v80, v81
	v_cvt_pk_bf16_f32 v125, v82, v83
	ds_read_b64_tr_b16 v[80:81], v192 offset:30720
	ds_read_b64_tr_b16 v[82:83], v192 offset:31232
	v_mfma_f32_32x32x16_bf16 v[48:63], v[160:163], v[120:123], v[48:63]
	v_add_f32_e32 v108, v86, v108
	v_add_f32_e32 v108, v87, v108
	v_add_f32_e32 v108, v88, v108
	v_add_f32_e32 v108, v89, v108
	v_cvt_pk_bf16_f32 v126, v84, v85
	v_cvt_pk_bf16_f32 v127, v86, v87
	ds_read_b64_tr_b16 v[84:85], v192 offset:27648
	ds_read_b64_tr_b16 v[86:87], v192 offset:28160
	v_mfma_f32_32x32x16_bf16 v[64:79], v[156:159], v[112:115], v[64:79]
	v_add_f32_e32 v108, v90, v108
	v_add_f32_e32 v108, v91, v108
	v_add_f32_e32 v108, v92, v108
	v_add_f32_e32 v108, v93, v108
	v_cvt_pk_bf16_f32 v116, v88, v89
	v_cvt_pk_bf16_f32 v117, v90, v91
	ds_read_b64_tr_b16 v[88:89], v192 offset:31744
	ds_read_b64_tr_b16 v[90:91], v192 offset:32256
	v_mfma_f32_32x32x16_bf16 v[48:63], v[152:155], v[112:115], v[48:63]
	v_add_f32_e32 v108, v94, v108
	v_add_f32_e32 v108, v95, v108
	v_cvt_pk_bf16_f32 v118, v92, v93
	v_cvt_pk_bf16_f32 v119, v94, v95
	s_mov_b64 s[44:45], 0x1490a000
	v_lshl_add_u64 v[92:93], v[186:187], 0, s[44:45]
	s_add_i32 s44, s68, s35
	s_mov_b32 m0, s44
	s_nop 0
	global_load_lds_dwordx4 v[92:93], off
	s_mov_b64 s[44:45], 0x15206000
	v_lshl_add_u64 v[92:93], v[188:189], 0, s[44:45]
	s_add_i32 s44, s60, s49
	s_mov_b32 m0, s44
	s_nop 0
	global_load_lds_dwordx4 v[92:93], off
	v_max_f32_e32 v92, v64, v65
	v_max3_f32 v93, v66, v67, v49
	v_max3_f32 v92, v92, v48, v50
	v_max3_f32 v92, v92, v51, v68
	v_max3_f32 v93, v93, v70, v71
	v_max3_f32 v92, v92, v69, v52
	v_max3_f32 v93, v93, v54, v55
	v_max3_f32 v92, v92, v53, v72
	v_max3_f32 v93, v93, v74, v75
	v_max3_f32 v92, v92, v73, v56
	v_max3_f32 v93, v93, v58, v59
	v_max3_f32 v92, v92, v57, v76
	v_max3_f32 v93, v93, v78, v79
	v_max3_f32 v92, v92, v77, v60
	v_max3_f32 v93, v93, v62, v63
	v_max3_f32 v92, v92, v61, v93
	v_mov_b32_e32 v93, v92
	s_nop 1
	v_permlane32_swap_b32_e32 v92, v93
	v_max_f32_e32 v92, v92, v93
	v_cmp_lt_f32_e32 vcc, s29, v92
	s_cmp_lg_u64 vcc, 0
	v_add_f32_e32 v192, v191, v108
	s_cselect_b64 s[44:45], -1, 0
	s_cbranch_vccnz .LBB0_655

.LBB0_721:
	v_mfma_f32_32x32x16_bf16 v[128:143], v[204:207], v[172:175], v[64:79]
	v_add_f32_e32 v112, v96, v97
	v_add_f32_e32 v112, v98, v112
	v_add_f32_e32 v112, v99, v112
	v_add_f32_e32 v112, v100, v112
	v_add_f32_e32 v112, v101, v112
	v_cvt_pk_bf16_f32 v160, v96, v97
	v_cvt_pk_bf16_f32 v161, v98, v99
	v_add_f32_e32 v96, v102, v112
	v_mfma_f32_32x32x16_bf16 v[112:127], v[200:203], v[172:175], v[64:79]
	v_add_f32_e32 v96, v103, v96
	v_add_f32_e32 v96, v104, v96
	v_add_f32_e32 v96, v105, v96
	v_cvt_pk_bf16_f32 v162, v100, v101
	v_cvt_pk_bf16_f32 v163, v102, v103
	v_mfma_f32_32x32x16_bf16 v[128:143], v[196:199], v[168:171], v[128:143]
	v_add_f32_e32 v96, v106, v96
	v_add_f32_e32 v96, v107, v96
	v_add_f32_e32 v96, v108, v96
	v_add_f32_e32 v96, v109, v96
	v_cvt_pk_bf16_f32 v152, v104, v105
	v_cvt_pk_bf16_f32 v153, v106, v107
	v_mfma_f32_32x32x16_bf16 v[112:127], v[192:195], v[168:171], v[112:127]
	v_add_f32_e32 v96, v110, v96
	v_add_f32_e32 v96, v111, v96
	v_add_f32_e32 v96, v80, v96
	v_add_f32_e32 v96, v81, v96
	v_cvt_pk_bf16_f32 v154, v108, v109
	v_cvt_pk_bf16_f32 v155, v110, v111
	v_mfma_f32_32x32x16_bf16 v[128:143], v[188:191], v[164:167], v[128:143]
	v_add_f32_e32 v96, v82, v96
	v_add_f32_e32 v96, v83, v96
	v_add_f32_e32 v96, v84, v96
	v_add_f32_e32 v96, v85, v96
	v_cvt_pk_bf16_f32 v148, v80, v81
	v_cvt_pk_bf16_f32 v149, v82, v83
	v_mfma_f32_32x32x16_bf16 v[112:127], v[184:187], v[164:167], v[112:127]
	v_add_f32_e32 v80, v86, v96
	v_add_f32_e32 v80, v87, v80
	v_add_f32_e32 v80, v88, v80
	v_add_f32_e32 v80, v89, v80
	v_cvt_pk_bf16_f32 v150, v84, v85
	v_cvt_pk_bf16_f32 v151, v86, v87
	v_mfma_f32_32x32x16_bf16 v[128:143], v[180:183], v[156:159], v[128:143]
	v_add_f32_e32 v80, v90, v80
	v_add_f32_e32 v80, v91, v80
	v_add_f32_e32 v80, v92, v80
	v_add_f32_e32 v80, v93, v80
	v_cvt_pk_bf16_f32 v144, v88, v89
	v_cvt_pk_bf16_f32 v145, v90, v91
	v_mfma_f32_32x32x16_bf16 v[112:127], v[176:179], v[156:159], v[112:127]
	v_add_f32_e32 v80, v94, v80
	v_add_f32_e32 v82, v95, v80
	v_cvt_pk_bf16_f32 v146, v92, v93
	v_cvt_pk_bf16_f32 v147, v94, v95
	s_movk_i32 s42, 0xe000
	s_mov_b32 s43, -1
	v_lshl_add_u64 v[80:81], v[214:215], 0, s[42:43]
	s_add_i32 s42, s71, s49
	s_mov_b32 m0, s42
	s_nop 0
	global_load_lds_dwordx4 v[80:81], off
	s_movk_i32 s42, 0xbf80
	s_mov_b32 s43, -1
	v_lshl_add_u64 v[80:81], v[212:213], 0, s[42:43]
	s_lshl_b32 s42, s61, 1
	s_add_i32 s44, s42, s60
	s_mov_b32 m0, s44
	s_nop 0
	global_load_lds_dwordx4 v[80:81], off
	s_movk_i32 s42, 0xc000
	s_mov_b32 s43, -1
	v_lshl_add_u64 v[80:81], v[212:213], 0, s[42:43]
	s_add_i32 s42, s44, 0x2000
	s_mov_b32 m0, s42
	s_nop 0
	global_load_lds_dwordx4 v[80:81], off
	v_max_f32_e32 v80, v128, v129
	v_max3_f32 v81, v130, v131, v113
	v_max3_f32 v80, v80, v112, v114
	v_max3_f32 v80, v80, v115, v132
	v_max3_f32 v81, v81, v134, v135
	v_max3_f32 v80, v80, v133, v116
	v_max3_f32 v81, v81, v118, v119
	v_max3_f32 v80, v80, v117, v136
	v_max3_f32 v81, v81, v138, v139
	v_max3_f32 v80, v80, v137, v120
	v_max3_f32 v81, v81, v122, v123
	v_max3_f32 v80, v80, v121, v140
	v_max3_f32 v81, v81, v142, v143
	v_max3_f32 v80, v80, v141, v124
	v_max3_f32 v81, v81, v126, v127
	v_max3_f32 v80, v80, v125, v81
	v_mov_b32_e32 v81, v80
	s_nop 1
	v_permlane32_swap_b32_e32 v80, v81
	v_max_f32_e32 v80, v80, v81
	v_cmp_lt_f32_e32 vcc, s29, v80
	s_cmp_lg_u64 vcc, 0
	v_add_f32_e32 v204, v252, v82
	s_cselect_b64 s[42:43], -1, 0
	s_cbranch_vccnz .LBB0_729

.LBB0_724:
	s_add_i32 s42, s61, 0x2000
	s_cmpk_lg_i32 s61, 0x4000
	s_cselect_b32 s65, s42, 0
	v_mfma_f32_32x32x16_bf16 v[96:111], v[80:83], v[172:175], v[64:79]
	v_add_f32_e32 v84, v128, v129
	v_add_f32_e32 v84, v130, v84
	v_add_f32_e32 v84, v131, v84
	v_add_f32_e32 v84, v132, v84
	v_add_f32_e32 v84, v133, v84
	v_cvt_pk_bf16_f32 v160, v128, v129
	v_cvt_pk_bf16_f32 v161, v130, v131
	v_add_f32_e32 v80, v134, v84
	v_add_f32_e32 v80, v135, v80
	v_add_f32_e32 v80, v136, v80
	v_add_f32_e32 v128, v137, v80
	v_mfma_f32_32x32x16_bf16 v[80:95], v[196:199], v[172:175], v[64:79]
	v_cvt_pk_bf16_f32 v162, v132, v133
	v_cvt_pk_bf16_f32 v163, v134, v135
	v_mfma_f32_32x32x16_bf16 v[96:111], v[200:203], v[168:171], v[96:111]
	v_add_f32_e32 v128, v138, v128
	v_add_f32_e32 v128, v139, v128
	v_add_f32_e32 v128, v140, v128
	v_add_f32_e32 v128, v141, v128
	v_cvt_pk_bf16_f32 v152, v136, v137
	v_cvt_pk_bf16_f32 v153, v138, v139
	v_mfma_f32_32x32x16_bf16 v[80:95], v[192:195], v[168:171], v[80:95]
	v_add_f32_e32 v128, v142, v128
	v_add_f32_e32 v128, v143, v128
	v_add_f32_e32 v128, v112, v128
	v_add_f32_e32 v128, v113, v128
	v_cvt_pk_bf16_f32 v154, v140, v141
	v_cvt_pk_bf16_f32 v155, v142, v143
	v_mfma_f32_32x32x16_bf16 v[96:111], v[188:191], v[164:167], v[96:111]
	v_add_f32_e32 v128, v114, v128
	v_add_f32_e32 v128, v115, v128
	v_add_f32_e32 v128, v116, v128
	v_add_f32_e32 v128, v117, v128
	v_cvt_pk_bf16_f32 v148, v112, v113
	v_cvt_pk_bf16_f32 v149, v114, v115
	v_mfma_f32_32x32x16_bf16 v[80:95], v[184:187], v[164:167], v[80:95]
	v_add_f32_e32 v112, v118, v128
	v_add_f32_e32 v112, v119, v112
	v_add_f32_e32 v112, v120, v112
	v_add_f32_e32 v112, v121, v112
	v_cvt_pk_bf16_f32 v150, v116, v117
	v_cvt_pk_bf16_f32 v151, v118, v119
	v_mfma_f32_32x32x16_bf16 v[96:111], v[180:183], v[156:159], v[96:111]
	v_add_f32_e32 v112, v122, v112
	v_add_f32_e32 v112, v123, v112
	v_add_f32_e32 v112, v124, v112
	v_add_f32_e32 v112, v125, v112
	v_cvt_pk_bf16_f32 v144, v120, v121
	v_cvt_pk_bf16_f32 v145, v122, v123
	v_mfma_f32_32x32x16_bf16 v[80:95], v[176:179], v[156:159], v[80:95]
	v_add_f32_e32 v112, v126, v112
	v_add_f32_e32 v114, v127, v112
	v_cvt_pk_bf16_f32 v146, v124, v125
	v_cvt_pk_bf16_f32 v147, v126, v127
	s_add_i32 s42, s61, s49
	s_mov_b32 m0, s42
	s_nop 0
	global_load_lds_dwordx4 v[214:215], off
	s_movk_i32 s42, 0xff80
	s_mov_b32 s43, -1
	v_lshl_add_u64 v[112:113], v[212:213], 0, s[42:43]
	s_lshl_b32 s42, s65, 1
	s_add_i32 s42, s42, s60
	s_mov_b32 m0, s42
	s_nop 0
	global_load_lds_dwordx4 v[112:113], off
	v_max_f32_e32 v112, v96, v97
	v_max3_f32 v113, v98, v99, v81
	v_max3_f32 v112, v112, v80, v82
	v_max3_f32 v112, v112, v83, v100
	v_max3_f32 v113, v113, v102, v103
	v_max3_f32 v112, v112, v101, v84
	v_max3_f32 v113, v113, v86, v87
	v_max3_f32 v112, v112, v85, v104
	v_max3_f32 v113, v113, v106, v107
	v_max3_f32 v112, v112, v105, v88
	v_max3_f32 v113, v113, v90, v91
	v_max3_f32 v112, v112, v89, v108
	v_max3_f32 v113, v113, v110, v111
	v_max3_f32 v112, v112, v109, v92
	v_max3_f32 v113, v113, v94, v95
	v_max3_f32 v112, v112, v93, v113
	v_mov_b32_e32 v113, v112
	s_nop 1
	v_permlane32_swap_b32_e32 v112, v113
	v_max_f32_e32 v112, v112, v113
	s_addk_i32 s42, 0x2000
	s_mov_b32 m0, s42
	s_nop 0
	global_load_lds_dwordx4 v[212:213], off
	v_cmp_lt_f32_e32 vcc, s29, v112
	s_cmp_lg_u64 vcc, 0
	v_add_f32_e32 v252, v204, v114
	s_cselect_b64 s[42:43], -1, 0
	s_cbranch_vccnz .LBB0_732
